# P0 K/V window shift copy de-serialised: all slice loads first, one wait, all stores
# baseline (speedup 1.0000x reference)
.LBB0_24:
	v_lshl_or_b32 v1, s4, 6, v2
	s_mov_b32 s6, 0xfe000
	v_cmp_gt_i32_e32 vcc, s6, v1
	s_and_saveexec_b64 s[8:9], vcc
	v_writelane_b32 v254, s36, 7
	s_load_dwordx2 s[52:53], s[0:1], 0xc0
	s_nop 0
	v_writelane_b32 v254, s37, 8
	v_writelane_b32 v254, s38, 9
	v_writelane_b32 v254, s39, 10
	v_writelane_b32 v254, s40, 11
	v_writelane_b32 v254, s41, 12
	v_writelane_b32 v254, s42, 13
	v_writelane_b32 v254, s43, 14
	v_writelane_b32 v254, s44, 15
	v_writelane_b32 v254, s45, 16
	v_writelane_b32 v254, s46, 17
	v_writelane_b32 v254, s47, 18
	v_writelane_b32 v254, s48, 19
	v_writelane_b32 v254, s49, 20
	v_writelane_b32 v254, s50, 21
	v_writelane_b32 v254, s51, 22
	s_nop 0
	v_readlane_b32 s50, v254, 0
	s_add_u32 s10, s80, 0x84c0000
	s_addc_u32 s11, s81, 0
	s_add_u32 s12, s80, 0x94c0000
	s_addc_u32 s13, s81, 0
	v_lshlrev_b32_e32 v47, 4, v2
	s_mov_b32 s15, s4
	s_cmp_ge_u32 s15, 0x3f80
	s_cbranch_scc1 .Lkvb_ld
	s_mul_i32 s16, s15, 0x8103
	s_lshr_b32 s16, s16, 22
	s_add_u32 s16, s16, s15
	s_lshl_b32 s16, s16, 10
	v_add_u32_e32 v48, s16, v47
	global_load_dwordx4 v[64:67], v48, s[40:41] offset:1024
	global_load_dwordx4 v[68:71], v48, s[42:43] offset:1024
	s_add_u32 s15, s15, s14
	s_cmp_ge_u32 s15, 0x3f80
	s_cbranch_scc1 .Lkvb_ld
	s_mul_i32 s16, s15, 0x8103
	s_lshr_b32 s16, s16, 22
	s_add_u32 s16, s16, s15
	s_lshl_b32 s16, s16, 10
	v_add_u32_e32 v49, s16, v47
	global_load_dwordx4 v[72:75], v49, s[40:41] offset:1024
	global_load_dwordx4 v[76:79], v49, s[42:43] offset:1024
	s_add_u32 s15, s15, s14
	s_cmp_ge_u32 s15, 0x3f80
	s_cbranch_scc1 .Lkvb_ld
	s_mul_i32 s16, s15, 0x8103
	s_lshr_b32 s16, s16, 22
	s_add_u32 s16, s16, s15
	s_lshl_b32 s16, s16, 10
	v_add_u32_e32 v50, s16, v47
	global_load_dwordx4 v[80:83], v50, s[40:41] offset:1024
	global_load_dwordx4 v[84:87], v50, s[42:43] offset:1024
	s_add_u32 s15, s15, s14
	s_cmp_ge_u32 s15, 0x3f80
	s_cbranch_scc1 .Lkvb_ld
	s_mul_i32 s16, s15, 0x8103
	s_lshr_b32 s16, s16, 22
	s_add_u32 s16, s16, s15
	s_lshl_b32 s16, s16, 10
	v_add_u32_e32 v51, s16, v47
	global_load_dwordx4 v[88:91], v51, s[40:41] offset:1024
	global_load_dwordx4 v[92:95], v51, s[42:43] offset:1024
	s_add_u32 s15, s15, s14
	s_cmp_ge_u32 s15, 0x3f80
	s_cbranch_scc1 .Lkvb_ld
	s_mul_i32 s16, s15, 0x8103
	s_lshr_b32 s16, s16, 22
	s_add_u32 s16, s16, s15
	s_lshl_b32 s16, s16, 10
	v_add_u32_e32 v52, s16, v47
	global_load_dwordx4 v[96:99], v52, s[40:41] offset:1024
	global_load_dwordx4 v[100:103], v52, s[42:43] offset:1024
	s_add_u32 s15, s15, s14
	s_cmp_ge_u32 s15, 0x3f80
	s_cbranch_scc1 .Lkvb_ld
	s_mul_i32 s16, s15, 0x8103
	s_lshr_b32 s16, s16, 22
	s_add_u32 s16, s16, s15
	s_lshl_b32 s16, s16, 10
	v_add_u32_e32 v53, s16, v47
	global_load_dwordx4 v[104:107], v53, s[40:41] offset:1024
	global_load_dwordx4 v[108:111], v53, s[42:43] offset:1024
	s_add_u32 s15, s15, s14
	s_cmp_ge_u32 s15, 0x3f80
	s_cbranch_scc1 .Lkvb_ld
	s_mul_i32 s16, s15, 0x8103
	s_lshr_b32 s16, s16, 22
	s_add_u32 s16, s16, s15
	s_lshl_b32 s16, s16, 10
	v_add_u32_e32 v54, s16, v47
	global_load_dwordx4 v[112:115], v54, s[40:41] offset:1024
	global_load_dwordx4 v[116:119], v54, s[42:43] offset:1024
	s_add_u32 s15, s15, s14
	s_cmp_ge_u32 s15, 0x3f80
	s_cbranch_scc1 .Lkvb_ld
	s_mul_i32 s16, s15, 0x8103
	s_lshr_b32 s16, s16, 22
	s_add_u32 s16, s16, s15
	s_lshl_b32 s16, s16, 10
	v_add_u32_e32 v55, s16, v47
	global_load_dwordx4 v[120:123], v55, s[40:41] offset:1024
	global_load_dwordx4 v[124:127], v55, s[42:43] offset:1024
	s_add_u32 s15, s15, s14
.Lkvb_ld:
	s_mov_b32 s15, s4
	s_waitcnt vmcnt(0)
	s_cmp_ge_u32 s15, 0x3f80
	s_cbranch_scc1 .Lkvb_st
	global_store_dwordx4 v48, v[64:67], s[10:11]
	global_store_dwordx4 v48, v[68:71], s[12:13]
	s_add_u32 s15, s15, s14
	s_cmp_ge_u32 s15, 0x3f80
	s_cbranch_scc1 .Lkvb_st
	global_store_dwordx4 v49, v[72:75], s[10:11]
	global_store_dwordx4 v49, v[76:79], s[12:13]
	s_add_u32 s15, s15, s14
	s_cmp_ge_u32 s15, 0x3f80
	s_cbranch_scc1 .Lkvb_st
	global_store_dwordx4 v50, v[80:83], s[10:11]
	global_store_dwordx4 v50, v[84:87], s[12:13]
	s_add_u32 s15, s15, s14
	s_cmp_ge_u32 s15, 0x3f80
	s_cbranch_scc1 .Lkvb_st
	global_store_dwordx4 v51, v[88:91], s[10:11]
	global_store_dwordx4 v51, v[92:95], s[12:13]
	s_add_u32 s15, s15, s14
	s_cmp_ge_u32 s15, 0x3f80
	s_cbranch_scc1 .Lkvb_st
	global_store_dwordx4 v52, v[96:99], s[10:11]
	global_store_dwordx4 v52, v[100:103], s[12:13]
	s_add_u32 s15, s15, s14
	s_cmp_ge_u32 s15, 0x3f80
	s_cbranch_scc1 .Lkvb_st
	global_store_dwordx4 v53, v[104:107], s[10:11]
	global_store_dwordx4 v53, v[108:111], s[12:13]
	s_add_u32 s15, s15, s14
	s_cmp_ge_u32 s15, 0x3f80
	s_cbranch_scc1 .Lkvb_st
	global_store_dwordx4 v54, v[112:115], s[10:11]
	global_store_dwordx4 v54, v[116:119], s[12:13]
	s_add_u32 s15, s15, s14
	s_cmp_ge_u32 s15, 0x3f80
	s_cbranch_scc1 .Lkvb_st
	global_store_dwordx4 v55, v[120:123], s[10:11]
	global_store_dwordx4 v55, v[124:127], s[12:13]
	s_add_u32 s15, s15, s14
.Lkvb_st:
.LBB0_32:
	s_or_b64 exec, exec, s[8:9]
	s_load_dwordx16 s[8:23], s[0:1], 0x40
	s_cmp_gt_i32 s4, 0x807f
	v_mbcnt_lo_u32_b32 v144, -1, 0
	s_waitcnt lgkmcnt(0)
	v_writelane_b32 v254, s8, 23
	s_nop 1
	v_writelane_b32 v254, s9, 24
	v_writelane_b32 v254, s10, 25
	v_writelane_b32 v254, s11, 26
	v_writelane_b32 v254, s12, 27
	v_writelane_b32 v254, s13, 28
	v_writelane_b32 v254, s14, 29
	v_writelane_b32 v254, s15, 30
	v_writelane_b32 v254, s16, 31
	v_writelane_b32 v254, s17, 32
	v_writelane_b32 v254, s18, 33
	v_writelane_b32 v254, s19, 34
	v_writelane_b32 v254, s20, 35
	v_writelane_b32 v254, s21, 36
	v_writelane_b32 v254, s22, 37
	v_writelane_b32 v254, s23, 38
	s_nop 0
	v_readlane_b32 s5, v254, 6
	s_cbranch_scc1 .LBB0_58
	v_mbcnt_hi_u32_b32 v3, -1, v144
	v_and_b32_e32 v1, 64, v3
	v_add_u32_e32 v4, 64, v1
	v_xor_b32_e32 v1, 1, v3
	v_cmp_lt_i32_e32 vcc, v1, v4
	v_xor_b32_e32 v5, 2, v3
	v_mov_b32_e32 v35, 0
	v_cndmask_b32_e32 v1, v3, v1, vcc
	v_cmp_lt_i32_e32 vcc, v5, v4
	s_add_u32 s16, s82, 0x40000
	s_mov_b64 s[0:1], 0x1d80000
	v_cndmask_b32_e32 v5, v3, v5, vcc
	v_lshlrev_b32_e32 v46, 2, v5
	v_xor_b32_e32 v5, 4, v3
	v_cmp_lt_i32_e32 vcc, v5, v4
	s_addc_u32 s17, s83, 0
	s_mov_b32 s13, 0
	v_cndmask_b32_e32 v5, v3, v5, vcc
	v_lshlrev_b32_e32 v47, 2, v5
	v_xor_b32_e32 v5, 8, v3
	v_cmp_lt_i32_e32 vcc, v5, v4
	v_lshlrev_b32_e32 v1, 2, v1
	v_mov_b32_e32 v51, 0x358637bd
	v_cndmask_b32_e32 v5, v3, v5, vcc
	v_lshlrev_b32_e32 v48, 2, v5
	v_xor_b32_e32 v5, 16, v3
	v_cmp_lt_i32_e32 vcc, v5, v4
	s_mov_b32 s18, 0xf800000
	v_mov_b32_e32 v52, 0x260
	v_cndmask_b32_e32 v5, v3, v5, vcc
	v_lshlrev_b32_e32 v49, 2, v5
	v_xor_b32_e32 v5, 32, v3
	v_cmp_lt_i32_e32 vcc, v5, v4
	s_nop 1
	v_cndmask_b32_e32 v3, v3, v5, vcc
	v_lshl_add_u64 v[4:5], s[82:83], 0, v[34:35]
	v_lshlrev_b32_e32 v50, 2, v3
	v_lshl_add_u64 v[36:37], v[4:5], 0, s[0:1]
	v_cmp_eq_u32_e64 s[0:1], 0, v2
	v_lshlrev_b32_e32 v34, 4, v2
	s_branch .LBB0_35
